# nt on RKVL GEMM epilogue bf16 stores (264 MB output)
# speedup vs baseline: 1.0167x; 1.0167x over previous
.LBB0_570:
	v_lshl_or_b32 v128, s46, 8, v194
	v_mov_b64_e32 v[126:127], s[0:1]
	s_waitcnt lgkmcnt(0)
	v_ashrrev_i32_e32 v129, 31, v128
	v_mad_i64_i32 v[126:127], s[18:19], v196, s63, v[126:127]
	v_lshl_add_u64 v[130:131], v[128:129], 1, v[126:127]
	s_and_b64 vcc, exec, s[42:43]
	v_cvt_pk_bf16_f32 v126, v120, v121
	v_cvt_pk_bf16_f32 v127, v122, v123
	global_store_dwordx4 v[130:131], v[124:127], off nt
	s_cbranch_vccnz .LBB0_572
	v_add_f32_e32 v116, v116, v116
	v_add_f32_e32 v117, v117, v117
	v_add_f32_e32 v118, v118, v118
	v_add_f32_e32 v119, v119, v119
	v_mul_f32_e32 v116, 0x3fb8aa3b, v116
	v_mul_f32_e32 v117, 0x3fb8aa3b, v117
	v_mul_f32_e32 v118, 0x3fb8aa3b, v118
	v_mul_f32_e32 v119, 0x3fb8aa3b, v119
	v_exp_f32_e32 v116, v116
	v_exp_f32_e32 v117, v117
	v_exp_f32_e32 v118, v118
	v_exp_f32_e32 v119, v119
	v_add_f32_e32 v116, 1.0, v116
	v_add_f32_e32 v117, 1.0, v117
	v_add_f32_e32 v118, 1.0, v118
	v_add_f32_e32 v119, 1.0, v119
	v_rcp_f32_e32 v116, v116
	v_rcp_f32_e32 v118, v118
	v_rcp_f32_e32 v119, v119
	v_rcp_f32_e32 v117, v117
	v_pk_fma_f32 v[118:119], v[118:119], -2.0, 1.0 op_sel_hi:[1,0,0]
	v_pk_fma_f32 v[116:117], v[116:117], -2.0, 1.0 op_sel_hi:[1,0,0]

.LBB0_578:
	s_and_b64 vcc, exec, s[42:43]
	v_cvt_pk_bf16_f32 v118, v112, v113
	v_cvt_pk_bf16_f32 v119, v114, v115
	global_store_dwordx4 v[130:131], v[116:119], off offset:64 nt
	s_cbranch_vccnz .LBB0_580
	v_add_f32_e32 v108, v108, v108
	v_add_f32_e32 v109, v109, v109
	v_add_f32_e32 v110, v110, v110
	v_add_f32_e32 v111, v111, v111
	v_mul_f32_e32 v108, 0x3fb8aa3b, v108
	v_mul_f32_e32 v109, 0x3fb8aa3b, v109
	v_mul_f32_e32 v110, 0x3fb8aa3b, v110
	v_mul_f32_e32 v111, 0x3fb8aa3b, v111
	v_exp_f32_e32 v108, v108
	v_exp_f32_e32 v109, v109
	v_exp_f32_e32 v110, v110
	v_exp_f32_e32 v111, v111
	v_add_f32_e32 v108, 1.0, v108
	v_add_f32_e32 v109, 1.0, v109
	v_add_f32_e32 v110, 1.0, v110
	v_add_f32_e32 v111, 1.0, v111
	v_rcp_f32_e32 v108, v108
	v_rcp_f32_e32 v110, v110
	v_rcp_f32_e32 v111, v111
	v_rcp_f32_e32 v109, v109
	v_pk_fma_f32 v[110:111], v[110:111], -2.0, 1.0 op_sel_hi:[1,0,0]
	v_pk_fma_f32 v[108:109], v[108:109], -2.0, 1.0 op_sel_hi:[1,0,0]

.LBB0_586:
	v_or_b32_e32 v112, 16, v196
	v_mov_b64_e32 v[110:111], s[0:1]
	v_mad_i64_i32 v[110:111], s[18:19], v112, s63, v[110:111]
	v_lshl_add_u64 v[112:113], v[128:129], 1, v[110:111]
	s_and_b64 vcc, exec, s[42:43]
	v_cvt_pk_bf16_f32 v110, v104, v105
	v_cvt_pk_bf16_f32 v111, v106, v107
	global_store_dwordx4 v[112:113], v[108:111], off nt
	s_cbranch_vccnz .LBB0_588
	v_add_f32_e32 v100, v100, v100
	v_add_f32_e32 v101, v101, v101
	v_add_f32_e32 v102, v102, v102
	v_add_f32_e32 v103, v103, v103
	v_mul_f32_e32 v100, 0x3fb8aa3b, v100
	v_mul_f32_e32 v101, 0x3fb8aa3b, v101
	v_mul_f32_e32 v102, 0x3fb8aa3b, v102
	v_mul_f32_e32 v103, 0x3fb8aa3b, v103
	v_exp_f32_e32 v100, v100
	v_exp_f32_e32 v101, v101
	v_exp_f32_e32 v102, v102
	v_exp_f32_e32 v103, v103
	v_add_f32_e32 v100, 1.0, v100
	v_add_f32_e32 v101, 1.0, v101
	v_add_f32_e32 v102, 1.0, v102
	v_add_f32_e32 v103, 1.0, v103
	v_rcp_f32_e32 v100, v100
	v_rcp_f32_e32 v102, v102
	v_rcp_f32_e32 v103, v103
	v_rcp_f32_e32 v101, v101
	v_pk_fma_f32 v[102:103], v[102:103], -2.0, 1.0 op_sel_hi:[1,0,0]
	v_pk_fma_f32 v[100:101], v[100:101], -2.0, 1.0 op_sel_hi:[1,0,0]

.LBB0_594:
	s_and_b64 vcc, exec, s[42:43]
	v_cvt_pk_bf16_f32 v102, v96, v97
	v_cvt_pk_bf16_f32 v103, v98, v99
	global_store_dwordx4 v[112:113], v[100:103], off offset:64 nt
	s_cbranch_vccnz .LBB0_596
	v_add_f32_e32 v92, v92, v92
	v_add_f32_e32 v93, v93, v93
	v_add_f32_e32 v94, v94, v94
	v_add_f32_e32 v95, v95, v95
	v_mul_f32_e32 v92, 0x3fb8aa3b, v92
	v_mul_f32_e32 v93, 0x3fb8aa3b, v93
	v_mul_f32_e32 v94, 0x3fb8aa3b, v94
	v_mul_f32_e32 v95, 0x3fb8aa3b, v95
	v_exp_f32_e32 v92, v92
	v_exp_f32_e32 v93, v93
	v_exp_f32_e32 v94, v94
	v_exp_f32_e32 v95, v95
	v_add_f32_e32 v92, 1.0, v92
	v_add_f32_e32 v93, 1.0, v93
	v_add_f32_e32 v94, 1.0, v94
	v_add_f32_e32 v95, 1.0, v95
	v_rcp_f32_e32 v92, v92
	v_rcp_f32_e32 v94, v94
	v_rcp_f32_e32 v95, v95
	v_rcp_f32_e32 v93, v93
	v_pk_fma_f32 v[94:95], v[94:95], -2.0, 1.0 op_sel_hi:[1,0,0]
	v_pk_fma_f32 v[92:93], v[92:93], -2.0, 1.0 op_sel_hi:[1,0,0]

.LBB0_602:
	v_or_b32_e32 v96, 32, v196
	v_mov_b64_e32 v[94:95], s[0:1]
	v_mad_i64_i32 v[94:95], s[18:19], v96, s63, v[94:95]
	v_lshl_add_u64 v[96:97], v[128:129], 1, v[94:95]
	s_and_b64 vcc, exec, s[42:43]
	v_cvt_pk_bf16_f32 v94, v88, v89
	v_cvt_pk_bf16_f32 v95, v90, v91
	global_store_dwordx4 v[96:97], v[92:95], off nt
	s_cbranch_vccnz .LBB0_604
	v_add_f32_e32 v84, v84, v84
	v_add_f32_e32 v85, v85, v85
	v_add_f32_e32 v86, v86, v86
	v_add_f32_e32 v87, v87, v87
	v_mul_f32_e32 v84, 0x3fb8aa3b, v84
	v_mul_f32_e32 v85, 0x3fb8aa3b, v85
	v_mul_f32_e32 v86, 0x3fb8aa3b, v86
	v_mul_f32_e32 v87, 0x3fb8aa3b, v87
	v_exp_f32_e32 v84, v84
	v_exp_f32_e32 v85, v85
	v_exp_f32_e32 v86, v86
	v_exp_f32_e32 v87, v87
	v_add_f32_e32 v84, 1.0, v84
	v_add_f32_e32 v85, 1.0, v85
	v_add_f32_e32 v86, 1.0, v86
	v_add_f32_e32 v87, 1.0, v87
	v_rcp_f32_e32 v84, v84
	v_rcp_f32_e32 v86, v86
	v_rcp_f32_e32 v87, v87
	v_rcp_f32_e32 v85, v85
	v_pk_fma_f32 v[86:87], v[86:87], -2.0, 1.0 op_sel_hi:[1,0,0]
	v_pk_fma_f32 v[84:85], v[84:85], -2.0, 1.0 op_sel_hi:[1,0,0]

.LBB0_610:
	s_and_b64 vcc, exec, s[42:43]
	v_cvt_pk_bf16_f32 v86, v80, v81
	v_cvt_pk_bf16_f32 v87, v82, v83
	global_store_dwordx4 v[96:97], v[84:87], off offset:64 nt
	s_cbranch_vccnz .LBB0_612
	v_add_f32_e32 v76, v76, v76
	v_add_f32_e32 v77, v77, v77
	v_add_f32_e32 v78, v78, v78
	v_add_f32_e32 v79, v79, v79
	v_mul_f32_e32 v76, 0x3fb8aa3b, v76
	v_mul_f32_e32 v77, 0x3fb8aa3b, v77
	v_mul_f32_e32 v78, 0x3fb8aa3b, v78
	v_mul_f32_e32 v79, 0x3fb8aa3b, v79
	v_exp_f32_e32 v76, v76
	v_exp_f32_e32 v77, v77
	v_exp_f32_e32 v78, v78
	v_exp_f32_e32 v79, v79
	v_add_f32_e32 v76, 1.0, v76
	v_add_f32_e32 v77, 1.0, v77
	v_add_f32_e32 v78, 1.0, v78
	v_add_f32_e32 v79, 1.0, v79
	v_rcp_f32_e32 v76, v76
	v_rcp_f32_e32 v78, v78
	v_rcp_f32_e32 v79, v79
	v_rcp_f32_e32 v77, v77
	v_pk_fma_f32 v[78:79], v[78:79], -2.0, 1.0 op_sel_hi:[1,0,0]
	v_pk_fma_f32 v[76:77], v[76:77], -2.0, 1.0 op_sel_hi:[1,0,0]

.LBB0_618:
	v_or_b32_e32 v80, 48, v196
	v_mov_b64_e32 v[78:79], s[0:1]
	v_mad_i64_i32 v[78:79], s[18:19], v80, s63, v[78:79]
	v_lshl_add_u64 v[80:81], v[128:129], 1, v[78:79]
	s_and_b64 vcc, exec, s[42:43]
	v_cvt_pk_bf16_f32 v78, v72, v73
	v_cvt_pk_bf16_f32 v79, v74, v75
	global_store_dwordx4 v[80:81], v[76:79], off nt
	s_cbranch_vccnz .LBB0_620
	v_add_f32_e32 v68, v68, v68
	v_add_f32_e32 v69, v69, v69
	v_add_f32_e32 v70, v70, v70
	v_add_f32_e32 v71, v71, v71
	v_mul_f32_e32 v68, 0x3fb8aa3b, v68
	v_mul_f32_e32 v69, 0x3fb8aa3b, v69
	v_mul_f32_e32 v70, 0x3fb8aa3b, v70
	v_mul_f32_e32 v71, 0x3fb8aa3b, v71
	v_exp_f32_e32 v68, v68
	v_exp_f32_e32 v69, v69
	v_exp_f32_e32 v70, v70
	v_exp_f32_e32 v71, v71
	v_add_f32_e32 v68, 1.0, v68
	v_add_f32_e32 v69, 1.0, v69
	v_add_f32_e32 v70, 1.0, v70
	v_add_f32_e32 v71, 1.0, v71
	v_rcp_f32_e32 v68, v68
	v_rcp_f32_e32 v70, v70
	v_rcp_f32_e32 v71, v71
	v_rcp_f32_e32 v69, v69
	v_pk_fma_f32 v[70:71], v[70:71], -2.0, 1.0 op_sel_hi:[1,0,0]
	v_pk_fma_f32 v[68:69], v[68:69], -2.0, 1.0 op_sel_hi:[1,0,0]

.LBB0_626:
	s_and_b64 vcc, exec, s[42:43]
	v_cvt_pk_bf16_f32 v70, v64, v65
	v_cvt_pk_bf16_f32 v71, v66, v67
	global_store_dwordx4 v[80:81], v[68:71], off offset:64 nt
	s_cbranch_vccnz .LBB0_628
	v_add_f32_e32 v60, v60, v60
	v_add_f32_e32 v61, v61, v61
	v_add_f32_e32 v62, v62, v62
	v_add_f32_e32 v63, v63, v63
	v_mul_f32_e32 v60, 0x3fb8aa3b, v60
	v_mul_f32_e32 v61, 0x3fb8aa3b, v61
	v_mul_f32_e32 v62, 0x3fb8aa3b, v62
	v_mul_f32_e32 v63, 0x3fb8aa3b, v63
	v_exp_f32_e32 v60, v60
	v_exp_f32_e32 v61, v61
	v_exp_f32_e32 v62, v62
	v_exp_f32_e32 v63, v63
	v_add_f32_e32 v60, 1.0, v60
	v_add_f32_e32 v61, 1.0, v61
	v_add_f32_e32 v62, 1.0, v62
	v_add_f32_e32 v63, 1.0, v63
	v_rcp_f32_e32 v60, v60
	v_rcp_f32_e32 v62, v62
	v_rcp_f32_e32 v63, v63
	v_rcp_f32_e32 v61, v61
	v_pk_fma_f32 v[62:63], v[62:63], -2.0, 1.0 op_sel_hi:[1,0,0]
	v_pk_fma_f32 v[60:61], v[60:61], -2.0, 1.0 op_sel_hi:[1,0,0]

.LBB0_634:
	v_add_u32_e32 v64, 0x80, v196
	v_mov_b64_e32 v[62:63], s[0:1]
	v_mad_i64_i32 v[62:63], s[18:19], v64, s63, v[62:63]
	v_lshl_add_u64 v[64:65], v[128:129], 1, v[62:63]
	s_and_b64 vcc, exec, s[42:43]
	v_cvt_pk_bf16_f32 v62, v56, v57
	v_cvt_pk_bf16_f32 v63, v58, v59
	global_store_dwordx4 v[64:65], v[60:63], off nt
	s_cbranch_vccnz .LBB0_636
	v_add_f32_e32 v52, v52, v52
	v_add_f32_e32 v53, v53, v53
	v_add_f32_e32 v54, v54, v54
	v_add_f32_e32 v55, v55, v55
	v_mul_f32_e32 v52, 0x3fb8aa3b, v52
	v_mul_f32_e32 v53, 0x3fb8aa3b, v53
	v_mul_f32_e32 v54, 0x3fb8aa3b, v54
	v_mul_f32_e32 v55, 0x3fb8aa3b, v55
	v_exp_f32_e32 v52, v52
	v_exp_f32_e32 v53, v53
	v_exp_f32_e32 v54, v54
	v_exp_f32_e32 v55, v55
	v_add_f32_e32 v52, 1.0, v52
	v_add_f32_e32 v53, 1.0, v53
	v_add_f32_e32 v54, 1.0, v54
	v_add_f32_e32 v55, 1.0, v55
	v_rcp_f32_e32 v52, v52
	v_rcp_f32_e32 v54, v54
	v_rcp_f32_e32 v55, v55
	v_rcp_f32_e32 v53, v53
	v_pk_fma_f32 v[54:55], v[54:55], -2.0, 1.0 op_sel_hi:[1,0,0]
	v_pk_fma_f32 v[52:53], v[52:53], -2.0, 1.0 op_sel_hi:[1,0,0]

.LBB0_642:
	s_and_b64 vcc, exec, s[42:43]
	v_cvt_pk_bf16_f32 v54, v48, v49
	v_cvt_pk_bf16_f32 v55, v50, v51
	global_store_dwordx4 v[64:65], v[52:55], off offset:64 nt
	s_cbranch_vccnz .LBB0_644
	v_add_f32_e32 v44, v44, v44
	v_add_f32_e32 v45, v45, v45
	v_add_f32_e32 v46, v46, v46
	v_add_f32_e32 v47, v47, v47
	v_mul_f32_e32 v44, 0x3fb8aa3b, v44
	v_mul_f32_e32 v45, 0x3fb8aa3b, v45
	v_mul_f32_e32 v46, 0x3fb8aa3b, v46
	v_mul_f32_e32 v47, 0x3fb8aa3b, v47
	v_exp_f32_e32 v44, v44
	v_exp_f32_e32 v45, v45
	v_exp_f32_e32 v46, v46
	v_exp_f32_e32 v47, v47
	v_add_f32_e32 v44, 1.0, v44
	v_add_f32_e32 v45, 1.0, v45
	v_add_f32_e32 v46, 1.0, v46
	v_add_f32_e32 v47, 1.0, v47
	v_rcp_f32_e32 v44, v44
	v_rcp_f32_e32 v46, v46
	v_rcp_f32_e32 v47, v47
	v_rcp_f32_e32 v45, v45
	v_pk_fma_f32 v[46:47], v[46:47], -2.0, 1.0 op_sel_hi:[1,0,0]
	v_pk_fma_f32 v[44:45], v[44:45], -2.0, 1.0 op_sel_hi:[1,0,0]

.LBB0_650:
	v_add_u32_e32 v48, 0x90, v196
	v_mov_b64_e32 v[46:47], s[0:1]
	v_mad_i64_i32 v[46:47], s[18:19], v48, s63, v[46:47]
	v_lshl_add_u64 v[48:49], v[128:129], 1, v[46:47]
	s_and_b64 vcc, exec, s[42:43]
	v_cvt_pk_bf16_f32 v46, v40, v41
	v_cvt_pk_bf16_f32 v47, v42, v43
	global_store_dwordx4 v[48:49], v[44:47], off nt
	s_cbranch_vccnz .LBB0_652
	v_add_f32_e32 v36, v36, v36
	v_add_f32_e32 v37, v37, v37
	v_add_f32_e32 v38, v38, v38
	v_add_f32_e32 v39, v39, v39
	v_mul_f32_e32 v36, 0x3fb8aa3b, v36
	v_mul_f32_e32 v37, 0x3fb8aa3b, v37
	v_mul_f32_e32 v38, 0x3fb8aa3b, v38
	v_mul_f32_e32 v39, 0x3fb8aa3b, v39
	v_exp_f32_e32 v36, v36
	v_exp_f32_e32 v37, v37
	v_exp_f32_e32 v38, v38
	v_exp_f32_e32 v39, v39
	v_add_f32_e32 v36, 1.0, v36
	v_add_f32_e32 v37, 1.0, v37
	v_add_f32_e32 v38, 1.0, v38
	v_add_f32_e32 v39, 1.0, v39
	v_rcp_f32_e32 v36, v36
	v_rcp_f32_e32 v38, v38
	v_rcp_f32_e32 v39, v39
	v_rcp_f32_e32 v37, v37
	v_pk_fma_f32 v[38:39], v[38:39], -2.0, 1.0 op_sel_hi:[1,0,0]
	v_pk_fma_f32 v[36:37], v[36:37], -2.0, 1.0 op_sel_hi:[1,0,0]

.LBB0_658:
	s_and_b64 vcc, exec, s[42:43]
	v_cvt_pk_bf16_f32 v38, v32, v33
	v_cvt_pk_bf16_f32 v39, v34, v35
	global_store_dwordx4 v[48:49], v[36:39], off offset:64 nt
	s_cbranch_vccnz .LBB0_660
	v_add_f32_e32 v28, v28, v28
	v_add_f32_e32 v29, v29, v29
	v_add_f32_e32 v30, v30, v30
	v_add_f32_e32 v31, v31, v31
	v_mul_f32_e32 v28, 0x3fb8aa3b, v28
	v_mul_f32_e32 v29, 0x3fb8aa3b, v29
	v_mul_f32_e32 v30, 0x3fb8aa3b, v30
	v_mul_f32_e32 v31, 0x3fb8aa3b, v31
	v_exp_f32_e32 v28, v28
	v_exp_f32_e32 v29, v29
	v_exp_f32_e32 v30, v30
	v_exp_f32_e32 v31, v31
	v_add_f32_e32 v28, 1.0, v28
	v_add_f32_e32 v29, 1.0, v29
	v_add_f32_e32 v30, 1.0, v30
	v_add_f32_e32 v31, 1.0, v31
	v_rcp_f32_e32 v28, v28
	v_rcp_f32_e32 v30, v30
	v_rcp_f32_e32 v31, v31
	v_rcp_f32_e32 v29, v29
	v_pk_fma_f32 v[30:31], v[30:31], -2.0, 1.0 op_sel_hi:[1,0,0]
	v_pk_fma_f32 v[28:29], v[28:29], -2.0, 1.0 op_sel_hi:[1,0,0]

.LBB0_666:
	v_add_u32_e32 v32, 0xa0, v196
	v_mov_b64_e32 v[30:31], s[0:1]
	v_mad_i64_i32 v[30:31], s[18:19], v32, s63, v[30:31]
	v_lshl_add_u64 v[32:33], v[128:129], 1, v[30:31]
	s_and_b64 vcc, exec, s[42:43]
	v_cvt_pk_bf16_f32 v30, v24, v25
	v_cvt_pk_bf16_f32 v31, v26, v27
	global_store_dwordx4 v[32:33], v[28:31], off nt
	s_cbranch_vccnz .LBB0_668
	v_add_f32_e32 v20, v20, v20
	v_add_f32_e32 v21, v21, v21
	v_add_f32_e32 v22, v22, v22
	v_add_f32_e32 v23, v23, v23
	v_mul_f32_e32 v20, 0x3fb8aa3b, v20
	v_mul_f32_e32 v21, 0x3fb8aa3b, v21
	v_mul_f32_e32 v22, 0x3fb8aa3b, v22
	v_mul_f32_e32 v23, 0x3fb8aa3b, v23
	v_exp_f32_e32 v20, v20
	v_exp_f32_e32 v21, v21
	v_exp_f32_e32 v22, v22
	v_exp_f32_e32 v23, v23
	v_add_f32_e32 v20, 1.0, v20
	v_add_f32_e32 v21, 1.0, v21
	v_add_f32_e32 v22, 1.0, v22
	v_add_f32_e32 v23, 1.0, v23
	v_rcp_f32_e32 v20, v20
	v_rcp_f32_e32 v22, v22
	v_rcp_f32_e32 v23, v23
	v_rcp_f32_e32 v21, v21
	v_pk_fma_f32 v[22:23], v[22:23], -2.0, 1.0 op_sel_hi:[1,0,0]
	v_pk_fma_f32 v[20:21], v[20:21], -2.0, 1.0 op_sel_hi:[1,0,0]

.LBB0_674:
	s_and_b64 vcc, exec, s[42:43]
	v_cvt_pk_bf16_f32 v22, v16, v17
	v_cvt_pk_bf16_f32 v23, v18, v19
	global_store_dwordx4 v[32:33], v[20:23], off offset:64 nt
	s_cbranch_vccnz .LBB0_676
	v_add_f32_e32 v12, v12, v12
	v_add_f32_e32 v13, v13, v13
	v_add_f32_e32 v14, v14, v14
	v_add_f32_e32 v15, v15, v15
	v_mul_f32_e32 v12, 0x3fb8aa3b, v12
	v_mul_f32_e32 v13, 0x3fb8aa3b, v13
	v_mul_f32_e32 v14, 0x3fb8aa3b, v14
	v_mul_f32_e32 v15, 0x3fb8aa3b, v15
	v_exp_f32_e32 v12, v12
	v_exp_f32_e32 v13, v13
	v_exp_f32_e32 v14, v14
	v_exp_f32_e32 v15, v15
	v_add_f32_e32 v12, 1.0, v12
	v_add_f32_e32 v13, 1.0, v13
	v_add_f32_e32 v14, 1.0, v14
	v_add_f32_e32 v15, 1.0, v15
	v_rcp_f32_e32 v12, v12
	v_rcp_f32_e32 v14, v14
	v_rcp_f32_e32 v15, v15
	v_rcp_f32_e32 v13, v13
	v_pk_fma_f32 v[14:15], v[14:15], -2.0, 1.0 op_sel_hi:[1,0,0]
	v_pk_fma_f32 v[12:13], v[12:13], -2.0, 1.0 op_sel_hi:[1,0,0]

.LBB0_682:
	v_add_u32_e32 v16, 0xb0, v196
	v_mov_b64_e32 v[14:15], s[0:1]
	v_mad_i64_i32 v[14:15], s[18:19], v16, s63, v[14:15]
	v_lshl_add_u64 v[16:17], v[128:129], 1, v[14:15]
	s_and_b64 vcc, exec, s[42:43]
	v_cvt_pk_bf16_f32 v14, v8, v9
	v_cvt_pk_bf16_f32 v15, v10, v11
	global_store_dwordx4 v[16:17], v[12:15], off nt
	s_cbranch_vccnz .LBB0_684
	v_add_f32_e32 v4, v4, v4
	v_add_f32_e32 v5, v5, v5
	v_add_f32_e32 v6, v6, v6
	v_add_f32_e32 v7, v7, v7
	v_mul_f32_e32 v4, 0x3fb8aa3b, v4
	v_mul_f32_e32 v5, 0x3fb8aa3b, v5
	v_mul_f32_e32 v6, 0x3fb8aa3b, v6
	v_mul_f32_e32 v7, 0x3fb8aa3b, v7
	v_exp_f32_e32 v4, v4
	v_exp_f32_e32 v5, v5
	v_exp_f32_e32 v6, v6
	v_exp_f32_e32 v7, v7
	v_add_f32_e32 v4, 1.0, v4
	v_add_f32_e32 v5, 1.0, v5
	v_add_f32_e32 v6, 1.0, v6
	v_add_f32_e32 v7, 1.0, v7
	v_rcp_f32_e32 v4, v4
	v_rcp_f32_e32 v6, v6
	v_rcp_f32_e32 v7, v7
	v_rcp_f32_e32 v5, v5
	v_pk_fma_f32 v[6:7], v[6:7], -2.0, 1.0 op_sel_hi:[1,0,0]
	v_pk_fma_f32 v[4:5], v[4:5], -2.0, 1.0 op_sel_hi:[1,0,0]

.LBB0_690:
	v_cvt_pk_bf16_f32 v6, v0, v1
	v_cvt_pk_bf16_f32 v7, v2, v3
	global_store_dwordx4 v[16:17], v[4:7], off offset:64 nt
